# sample diff units: loader waves rewritten with three register sets (three f32 cache tiles in flight instead of two), scalar-base addressing, same LDS images and barrier sequence
# speedup vs baseline: 1.0032x; 1.0011x over previous
;     ...
;         const int lt = tid - 256;
;         const int key0 = lt >> 5, q16 = lt & 31, cch = q16 >> 1, hlf = q16 & 1;
;         const char* kg = (const char*)(C.cdk + ((size_t)b * PAST * 4 + h) * 128) + (size_t)key0 * 2048 + q16 * 16;
;         const char* vg = (const char*)(C.cdv + ((size_t)b * PAST * 4 + h) * 128) + (size_t)key0 * 2048 + q16 * 16;
;         const int kd0 = (cch >> 3) * 8192 + (cch & 7) * 1024 + ((key0 ^ (cch & 7)) & 63) * 16 + hlf * 8;
;         const int vd0 = S2_V + (cch >> 2) * 4096 + key0 * 64 + (cch & 3) * 16 + hlf * 8;
;         v4u kA[8], vA[8], kB[8], vB[8];
;     ...
;         S2LOAD(kA, vA, 0); S2LOAD(kB, vB, 1);
;         S2WRITE(kA, vA, 0); S2LOAD(kA, vA, 2);
; template <int KIND>
; __device__ __forceinline__ void attn_queue(const AttnCtx& C, unsigned* head, int nunits, LAS unsigned char* lds) {
;     ...
;         __syncthreads();
;         if (threadIdx.x == 0) slot[0] = __hip_atomic_fetch_add(head, 1u, __ATOMIC_RELAXED, __HIP_MEMORY_SCOPE_AGENT);
;         __syncthreads();
;         const unsigned u = slot[0];
;         if (u >= (unsigned)nunits) break;
.LBB0_299:
	s_or_b64 exec, exec, s[2:3]
	s_waitcnt lgkmcnt(0)
	s_barrier
	ds_read_b32 v2, v205
	s_movk_i32 s2, 0x7f
	s_waitcnt lgkmcnt(0)
	v_cmp_lt_u32_e32 vcc, s2, v2
	s_mov_b64 s[2:3], -1
	s_cbranch_vccnz .LBB0_294
	v_mov_b32_e32 v140, v0
	v_and_b32_e32 v142, 3, v2
	v_readfirstlane_b32 s5, v140
	s_ashr_i32 s4, s5, 6
	s_cmp_lt_i32 s4, 4
	v_and_b32_e32 v208, 31, v140
	v_lshrrev_b32_e32 v207, 2, v2
	s_cselect_b64 s[10:11], -1, 0
	s_cmp_gt_i32 s4, 3
	v_lshlrev_b32_e32 v206, 7, v142
	v_lshlrev_b32_e32 v141, 3, v140
	s_barrier
	s_cbranch_scc0 .LBB0_304
	v_add_u32_e32 v223, 0xffffff00, v140
	v_lshrrev_b32_e32 v224, 5, v223
	v_and_b32_e32 v225, 31, v223
	v_lshlrev_b32_e32 v209, 11, v224
	v_lshl_or_b32 v209, v225, 4, v209
	v_add_u32_e32 v210, 0x4000, v209
	v_add_u32_e32 v211, 0x8000, v209
	v_add_u32_e32 v212, 0xc000, v209
	v_add_u32_e32 v213, 0x10000, v209
	v_add_u32_e32 v214, 0x14000, v209
	v_add_u32_e32 v215, 0x18000, v209
	v_add_u32_e32 v218, 0x1c000, v209
	v_lshrrev_b32_e32 v138, 1, v225
	v_and_b32_e32 v139, 1, v225
	v_lshlrev_b32_e32 v139, 3, v139
	v_lshrrev_b32_e32 v143, 3, v138
	v_lshlrev_b32_e32 v143, 13, v143
	v_and_b32_e32 v202, 7, v138
	v_lshl_or_b32 v143, v202, 10, v143
	v_xor_b32_e32 v203, v224, v202
	v_and_b32_e32 v203, 63, v203
	v_lshl_or_b32 v143, v203, 4, v143
	v_or_b32_e32 v221, v143, v139
	v_lshrrev_b32_e32 v143, 2, v138
	v_lshlrev_b32_e32 v143, 12, v143
	v_lshl_or_b32 v143, v224, 6, v143
	v_and_b32_e32 v202, 3, v138
	v_lshl_or_b32 v143, v202, 4, v143
	v_or_b32_e32 v143, v143, v139
	v_add_u32_e32 v222, 0x4000, v143
	v_readfirstlane_b32 s2, v207
	v_readfirstlane_b32 s3, v142
	v_readlane_b32 s70, v253, 17
	v_readlane_b32 s71, v253, 18
	v_readlane_b32 s72, v253, 19
	v_readlane_b32 s73, v253, 20
	s_lshl_b32 s6, s2, 23
	s_lshl_b32 s12, s3, 9
	s_add_i32 s6, s6, s12
	s_add_u32 s70, s70, s6
	s_addc_u32 s71, s71, 0
	s_add_u32 s72, s72, s6
	s_addc_u32 s73, s73, 0
	s_mov_b32 s60, 0
	global_load_dwordx4 v[2:5], v209, s[70:71] nt
	global_load_dwordx4 v[6:9], v210, s[70:71] nt
	global_load_dwordx4 v[10:13], v211, s[70:71] nt
	global_load_dwordx4 v[14:17], v212, s[70:71] nt
	global_load_dwordx4 v[18:21], v213, s[70:71] nt
	global_load_dwordx4 v[22:25], v214, s[70:71] nt
	global_load_dwordx4 v[26:29], v215, s[70:71] nt
	global_load_dwordx4 v[30:33], v218, s[70:71] nt
	global_load_dwordx4 v[34:37], v209, s[72:73] nt
	global_load_dwordx4 v[38:41], v210, s[72:73] nt
	global_load_dwordx4 v[42:45], v211, s[72:73] nt
	global_load_dwordx4 v[46:49], v212, s[72:73] nt
	global_load_dwordx4 v[50:53], v213, s[72:73] nt
	global_load_dwordx4 v[54:57], v214, s[72:73] nt
	global_load_dwordx4 v[58:61], v215, s[72:73] nt
	global_load_dwordx4 v[62:65], v218, s[72:73] nt
	s_add_u32 s70, s70, 0x20000
	s_addc_u32 s71, s71, 0
	s_add_u32 s72, s72, 0x20000
	s_addc_u32 s73, s73, 0
	global_load_dwordx4 v[66:69], v209, s[70:71] nt
	global_load_dwordx4 v[70:73], v210, s[70:71] nt
	global_load_dwordx4 v[74:77], v211, s[70:71] nt
	global_load_dwordx4 v[78:81], v212, s[70:71] nt
	global_load_dwordx4 v[82:85], v213, s[70:71] nt
	global_load_dwordx4 v[86:89], v214, s[70:71] nt
	global_load_dwordx4 v[90:93], v215, s[70:71] nt
	global_load_dwordx4 v[94:97], v218, s[70:71] nt
	global_load_dwordx4 v[98:101], v209, s[72:73] nt
	global_load_dwordx4 v[102:105], v210, s[72:73] nt
	global_load_dwordx4 v[106:109], v211, s[72:73] nt
	global_load_dwordx4 v[110:113], v212, s[72:73] nt
	global_load_dwordx4 v[114:117], v213, s[72:73] nt
	global_load_dwordx4 v[118:121], v214, s[72:73] nt
	global_load_dwordx4 v[122:125], v215, s[72:73] nt
	global_load_dwordx4 v[126:129], v218, s[72:73] nt
	s_add_u32 s70, s70, 0x20000
	s_addc_u32 s71, s71, 0
	s_add_u32 s72, s72, 0x20000
	s_addc_u32 s73, s73, 0
	global_load_dwordx4 v[130:133], v209, s[70:71] nt
	global_load_dwordx4 v[134:137], v210, s[70:71] nt
	global_load_dwordx4 v[144:147], v211, s[70:71] nt
	global_load_dwordx4 v[148:151], v212, s[70:71] nt
	global_load_dwordx4 v[152:155], v213, s[70:71] nt
	global_load_dwordx4 v[156:159], v214, s[70:71] nt
	global_load_dwordx4 v[160:163], v215, s[70:71] nt
	global_load_dwordx4 v[164:167], v218, s[70:71] nt
	global_load_dwordx4 v[168:171], v209, s[72:73] nt
	global_load_dwordx4 v[172:175], v210, s[72:73] nt
	global_load_dwordx4 v[176:179], v211, s[72:73] nt
	global_load_dwordx4 v[180:183], v212, s[72:73] nt
	global_load_dwordx4 v[184:187], v213, s[72:73] nt
	global_load_dwordx4 v[188:191], v214, s[72:73] nt
	global_load_dwordx4 v[192:195], v215, s[72:73] nt
	global_load_dwordx4 v[196:199], v218, s[72:73] nt
	s_add_u32 s70, s70, 0x20000
	s_addc_u32 s71, s71, 0
	s_add_u32 s72, s72, 0x20000
	s_addc_u32 s73, s73, 0
	s_and_b32 s61, s60, 3
	s_lshl_b32 s61, s61, 15
	s_add_i32 s60, s60, 1
	v_add_u32_e32 v219, s61, v221
	v_add_u32_e32 v220, s61, v222
	s_waitcnt vmcnt(40)
	v_cvt_pk_bf16_f32 v2, v2, v3
	v_cvt_pk_bf16_f32 v3, v4, v5
	ds_write_b64 v219, v[2:3]
	v_cvt_pk_bf16_f32 v6, v6, v7
	v_cvt_pk_bf16_f32 v7, v8, v9
	ds_write_b64 v219, v[6:7] offset:128
	v_cvt_pk_bf16_f32 v10, v10, v11
	v_cvt_pk_bf16_f32 v11, v12, v13
	ds_write_b64 v219, v[10:11] offset:256
	v_cvt_pk_bf16_f32 v14, v14, v15
	v_cvt_pk_bf16_f32 v15, v16, v17
	ds_write_b64 v219, v[14:15] offset:384
	v_cvt_pk_bf16_f32 v18, v18, v19
	v_cvt_pk_bf16_f32 v19, v20, v21
	ds_write_b64 v219, v[18:19] offset:512
	v_cvt_pk_bf16_f32 v22, v22, v23
	v_cvt_pk_bf16_f32 v23, v24, v25
	ds_write_b64 v219, v[22:23] offset:640
	v_cvt_pk_bf16_f32 v26, v26, v27
	v_cvt_pk_bf16_f32 v27, v28, v29
	ds_write_b64 v219, v[26:27] offset:768
	v_cvt_pk_bf16_f32 v30, v30, v31
	v_cvt_pk_bf16_f32 v31, v32, v33
	ds_write_b64 v219, v[30:31] offset:896
	s_waitcnt vmcnt(32)
; #define S2BAR() asm volatile("s_waitcnt lgkmcnt(0)\n\ts_barrier" ::: "memory")
;     ...
;         S2LOAD(kA, vA, 0); S2LOAD(kB, vB, 1);
;         S2WRITE(kA, vA, 0); S2LOAD(kA, vA, 2);
;         S2WRITE(kB, vB, 1); S2LOAD(kB, vB, 3);
;         S2BAR();
	v_cvt_pk_bf16_f32 v34, v34, v35
	v_cvt_pk_bf16_f32 v35, v36, v37
	ds_write_b64 v220, v[34:35]
	v_cvt_pk_bf16_f32 v38, v38, v39
	v_cvt_pk_bf16_f32 v39, v40, v41
	ds_write_b64 v220, v[38:39] offset:512
	v_cvt_pk_bf16_f32 v42, v42, v43
	v_cvt_pk_bf16_f32 v43, v44, v45
	ds_write_b64 v220, v[42:43] offset:1024
	v_cvt_pk_bf16_f32 v46, v46, v47
	v_cvt_pk_bf16_f32 v47, v48, v49
	ds_write_b64 v220, v[46:47] offset:1536
	v_cvt_pk_bf16_f32 v50, v50, v51
	v_cvt_pk_bf16_f32 v51, v52, v53
	ds_write_b64 v220, v[50:51] offset:2048
	v_cvt_pk_bf16_f32 v54, v54, v55
	v_cvt_pk_bf16_f32 v55, v56, v57
	ds_write_b64 v220, v[54:55] offset:2560
	v_cvt_pk_bf16_f32 v58, v58, v59
	v_cvt_pk_bf16_f32 v59, v60, v61
	ds_write_b64 v220, v[58:59] offset:3072
	v_cvt_pk_bf16_f32 v62, v62, v63
	v_cvt_pk_bf16_f32 v63, v64, v65
	ds_write_b64 v220, v[62:63] offset:3584
	global_load_dwordx4 v[2:5], v209, s[70:71] nt
	global_load_dwordx4 v[6:9], v210, s[70:71] nt
	global_load_dwordx4 v[10:13], v211, s[70:71] nt
	global_load_dwordx4 v[14:17], v212, s[70:71] nt
	global_load_dwordx4 v[18:21], v213, s[70:71] nt
	global_load_dwordx4 v[22:25], v214, s[70:71] nt
	global_load_dwordx4 v[26:29], v215, s[70:71] nt
	global_load_dwordx4 v[30:33], v218, s[70:71] nt
	global_load_dwordx4 v[34:37], v209, s[72:73] nt
	global_load_dwordx4 v[38:41], v210, s[72:73] nt
	global_load_dwordx4 v[42:45], v211, s[72:73] nt
	global_load_dwordx4 v[46:49], v212, s[72:73] nt
	global_load_dwordx4 v[50:53], v213, s[72:73] nt
	global_load_dwordx4 v[54:57], v214, s[72:73] nt
	global_load_dwordx4 v[58:61], v215, s[72:73] nt
	global_load_dwordx4 v[62:65], v218, s[72:73] nt
	s_add_u32 s70, s70, 0x20000
	s_addc_u32 s71, s71, 0
	s_add_u32 s72, s72, 0x20000
	s_addc_u32 s73, s73, 0
	s_and_b32 s61, s60, 3
	s_lshl_b32 s61, s61, 15
	s_add_i32 s60, s60, 1
	v_add_u32_e32 v219, s61, v221
	v_add_u32_e32 v220, s61, v222
	s_waitcnt vmcnt(40)
	v_cvt_pk_bf16_f32 v66, v66, v67
	v_cvt_pk_bf16_f32 v67, v68, v69
	ds_write_b64 v219, v[66:67]
	v_cvt_pk_bf16_f32 v70, v70, v71
	v_cvt_pk_bf16_f32 v71, v72, v73
	ds_write_b64 v219, v[70:71] offset:128
	v_cvt_pk_bf16_f32 v74, v74, v75
	v_cvt_pk_bf16_f32 v75, v76, v77
	ds_write_b64 v219, v[74:75] offset:256
	v_cvt_pk_bf16_f32 v78, v78, v79
	v_cvt_pk_bf16_f32 v79, v80, v81
	ds_write_b64 v219, v[78:79] offset:384
	v_cvt_pk_bf16_f32 v82, v82, v83
	v_cvt_pk_bf16_f32 v83, v84, v85
	ds_write_b64 v219, v[82:83] offset:512
	v_cvt_pk_bf16_f32 v86, v86, v87
	v_cvt_pk_bf16_f32 v87, v88, v89
	ds_write_b64 v219, v[86:87] offset:640
	v_cvt_pk_bf16_f32 v90, v90, v91
	v_cvt_pk_bf16_f32 v91, v92, v93
	ds_write_b64 v219, v[90:91] offset:768
	v_cvt_pk_bf16_f32 v94, v94, v95
	v_cvt_pk_bf16_f32 v95, v96, v97
	ds_write_b64 v219, v[94:95] offset:896
	s_waitcnt vmcnt(32)
	v_cvt_pk_bf16_f32 v98, v98, v99
	v_cvt_pk_bf16_f32 v99, v100, v101
	ds_write_b64 v220, v[98:99]
	v_cvt_pk_bf16_f32 v102, v102, v103
	v_cvt_pk_bf16_f32 v103, v104, v105
	ds_write_b64 v220, v[102:103] offset:512
	v_cvt_pk_bf16_f32 v106, v106, v107
	v_cvt_pk_bf16_f32 v107, v108, v109
	ds_write_b64 v220, v[106:107] offset:1024
	v_cvt_pk_bf16_f32 v110, v110, v111
	v_cvt_pk_bf16_f32 v111, v112, v113
	ds_write_b64 v220, v[110:111] offset:1536
	v_cvt_pk_bf16_f32 v114, v114, v115
	v_cvt_pk_bf16_f32 v115, v116, v117
	ds_write_b64 v220, v[114:115] offset:2048
	v_cvt_pk_bf16_f32 v118, v118, v119
	v_cvt_pk_bf16_f32 v119, v120, v121
	ds_write_b64 v220, v[118:119] offset:2560
	v_cvt_pk_bf16_f32 v122, v122, v123
	v_cvt_pk_bf16_f32 v123, v124, v125
	ds_write_b64 v220, v[122:123] offset:3072
	v_cvt_pk_bf16_f32 v126, v126, v127
	v_cvt_pk_bf16_f32 v127, v128, v129
	ds_write_b64 v220, v[126:127] offset:3584
	global_load_dwordx4 v[66:69], v209, s[70:71] nt
	global_load_dwordx4 v[70:73], v210, s[70:71] nt
	global_load_dwordx4 v[74:77], v211, s[70:71] nt
	global_load_dwordx4 v[78:81], v212, s[70:71] nt
	global_load_dwordx4 v[82:85], v213, s[70:71] nt
	global_load_dwordx4 v[86:89], v214, s[70:71] nt
	global_load_dwordx4 v[90:93], v215, s[70:71] nt
	global_load_dwordx4 v[94:97], v218, s[70:71] nt
	global_load_dwordx4 v[98:101], v209, s[72:73] nt
	global_load_dwordx4 v[102:105], v210, s[72:73] nt
	global_load_dwordx4 v[106:109], v211, s[72:73] nt
	global_load_dwordx4 v[110:113], v212, s[72:73] nt
	global_load_dwordx4 v[114:117], v213, s[72:73] nt
	global_load_dwordx4 v[118:121], v214, s[72:73] nt
	global_load_dwordx4 v[122:125], v215, s[72:73] nt
	global_load_dwordx4 v[126:129], v218, s[72:73] nt
	s_add_u32 s70, s70, 0x20000
	s_addc_u32 s71, s71, 0
	s_add_u32 s72, s72, 0x20000
	s_addc_u32 s73, s73, 0
	s_waitcnt lgkmcnt(0)
	s_barrier
	s_mov_b32 s62, 19
; #define S2BAR() asm volatile("s_waitcnt lgkmcnt(0)\n\ts_barrier" ::: "memory")
;     ...
;         S2LOAD(kA, vA, 0); S2LOAD(kB, vB, 1);
;         S2WRITE(kA, vA, 0); S2LOAD(kA, vA, 2);
;         S2WRITE(kB, vB, 1); S2LOAD(kB, vB, 3);
;         S2BAR();
;         for (int i = 0; i < 60; i += 2) {
;             S2WRITE(kA, vA, i + 2); S2LOAD(kA, vA, i + 4); S2BAR();
;             S2WRITE(kB, vB, i + 3); S2LOAD(kB, vB, i + 5); S2BAR();
;         }
.Ls2ld_loop_0:
	s_and_b32 s61, s60, 3
	s_lshl_b32 s61, s61, 15
	s_add_i32 s60, s60, 1
	v_add_u32_e32 v219, s61, v221
	v_add_u32_e32 v220, s61, v222
	s_waitcnt vmcnt(40)
	v_cvt_pk_bf16_f32 v130, v130, v131
	v_cvt_pk_bf16_f32 v131, v132, v133
	ds_write_b64 v219, v[130:131]
	v_cvt_pk_bf16_f32 v134, v134, v135
	v_cvt_pk_bf16_f32 v135, v136, v137
	ds_write_b64 v219, v[134:135] offset:128
	v_cvt_pk_bf16_f32 v144, v144, v145
	v_cvt_pk_bf16_f32 v145, v146, v147
	ds_write_b64 v219, v[144:145] offset:256
	v_cvt_pk_bf16_f32 v148, v148, v149
	v_cvt_pk_bf16_f32 v149, v150, v151
	ds_write_b64 v219, v[148:149] offset:384
	v_cvt_pk_bf16_f32 v152, v152, v153
	v_cvt_pk_bf16_f32 v153, v154, v155
	ds_write_b64 v219, v[152:153] offset:512
	v_cvt_pk_bf16_f32 v156, v156, v157
	v_cvt_pk_bf16_f32 v157, v158, v159
	ds_write_b64 v219, v[156:157] offset:640
	v_cvt_pk_bf16_f32 v160, v160, v161
	v_cvt_pk_bf16_f32 v161, v162, v163
	ds_write_b64 v219, v[160:161] offset:768
	v_cvt_pk_bf16_f32 v164, v164, v165
	v_cvt_pk_bf16_f32 v165, v166, v167
	ds_write_b64 v219, v[164:165] offset:896
	s_waitcnt vmcnt(32)
	v_cvt_pk_bf16_f32 v168, v168, v169
	v_cvt_pk_bf16_f32 v169, v170, v171
	ds_write_b64 v220, v[168:169]
	v_cvt_pk_bf16_f32 v172, v172, v173
	v_cvt_pk_bf16_f32 v173, v174, v175
	ds_write_b64 v220, v[172:173] offset:512
	v_cvt_pk_bf16_f32 v176, v176, v177
	v_cvt_pk_bf16_f32 v177, v178, v179
	ds_write_b64 v220, v[176:177] offset:1024
	v_cvt_pk_bf16_f32 v180, v180, v181
	v_cvt_pk_bf16_f32 v181, v182, v183
	ds_write_b64 v220, v[180:181] offset:1536
	v_cvt_pk_bf16_f32 v184, v184, v185
	v_cvt_pk_bf16_f32 v185, v186, v187
	ds_write_b64 v220, v[184:185] offset:2048
	v_cvt_pk_bf16_f32 v188, v188, v189
	v_cvt_pk_bf16_f32 v189, v190, v191
	ds_write_b64 v220, v[188:189] offset:2560
	v_cvt_pk_bf16_f32 v192, v192, v193
	v_cvt_pk_bf16_f32 v193, v194, v195
	ds_write_b64 v220, v[192:193] offset:3072
	v_cvt_pk_bf16_f32 v196, v196, v197
	v_cvt_pk_bf16_f32 v197, v198, v199
	ds_write_b64 v220, v[196:197] offset:3584
	global_load_dwordx4 v[130:133], v209, s[70:71] nt
	global_load_dwordx4 v[134:137], v210, s[70:71] nt
	global_load_dwordx4 v[144:147], v211, s[70:71] nt
	global_load_dwordx4 v[148:151], v212, s[70:71] nt
	global_load_dwordx4 v[152:155], v213, s[70:71] nt
	global_load_dwordx4 v[156:159], v214, s[70:71] nt
	global_load_dwordx4 v[160:163], v215, s[70:71] nt
	global_load_dwordx4 v[164:167], v218, s[70:71] nt
	global_load_dwordx4 v[168:171], v209, s[72:73] nt
	global_load_dwordx4 v[172:175], v210, s[72:73] nt
	global_load_dwordx4 v[176:179], v211, s[72:73] nt
	global_load_dwordx4 v[180:183], v212, s[72:73] nt
	global_load_dwordx4 v[184:187], v213, s[72:73] nt
	global_load_dwordx4 v[188:191], v214, s[72:73] nt
	global_load_dwordx4 v[192:195], v215, s[72:73] nt
	global_load_dwordx4 v[196:199], v218, s[72:73] nt
	s_add_u32 s70, s70, 0x20000
	s_addc_u32 s71, s71, 0
	s_add_u32 s72, s72, 0x20000
	s_addc_u32 s73, s73, 0
	s_waitcnt lgkmcnt(0)
	s_barrier
	s_and_b32 s61, s60, 3
	s_lshl_b32 s61, s61, 15
	s_add_i32 s60, s60, 1
	v_add_u32_e32 v219, s61, v221
	v_add_u32_e32 v220, s61, v222
	s_waitcnt vmcnt(40)
	v_cvt_pk_bf16_f32 v2, v2, v3
	v_cvt_pk_bf16_f32 v3, v4, v5
	ds_write_b64 v219, v[2:3]
	v_cvt_pk_bf16_f32 v6, v6, v7
	v_cvt_pk_bf16_f32 v7, v8, v9
	ds_write_b64 v219, v[6:7] offset:128
	v_cvt_pk_bf16_f32 v10, v10, v11
	v_cvt_pk_bf16_f32 v11, v12, v13
	ds_write_b64 v219, v[10:11] offset:256
	v_cvt_pk_bf16_f32 v14, v14, v15
	v_cvt_pk_bf16_f32 v15, v16, v17
	ds_write_b64 v219, v[14:15] offset:384
	v_cvt_pk_bf16_f32 v18, v18, v19
	v_cvt_pk_bf16_f32 v19, v20, v21
	ds_write_b64 v219, v[18:19] offset:512
	v_cvt_pk_bf16_f32 v22, v22, v23
	v_cvt_pk_bf16_f32 v23, v24, v25
	ds_write_b64 v219, v[22:23] offset:640
	v_cvt_pk_bf16_f32 v26, v26, v27
	v_cvt_pk_bf16_f32 v27, v28, v29
	ds_write_b64 v219, v[26:27] offset:768
	v_cvt_pk_bf16_f32 v30, v30, v31
	v_cvt_pk_bf16_f32 v31, v32, v33
	ds_write_b64 v219, v[30:31] offset:896
	s_waitcnt vmcnt(32)
	v_cvt_pk_bf16_f32 v34, v34, v35
	v_cvt_pk_bf16_f32 v35, v36, v37
	ds_write_b64 v220, v[34:35]
	v_cvt_pk_bf16_f32 v38, v38, v39
	v_cvt_pk_bf16_f32 v39, v40, v41
	ds_write_b64 v220, v[38:39] offset:512
	v_cvt_pk_bf16_f32 v42, v42, v43
	v_cvt_pk_bf16_f32 v43, v44, v45
	ds_write_b64 v220, v[42:43] offset:1024
	v_cvt_pk_bf16_f32 v46, v46, v47
	v_cvt_pk_bf16_f32 v47, v48, v49
	ds_write_b64 v220, v[46:47] offset:1536
	v_cvt_pk_bf16_f32 v50, v50, v51
	v_cvt_pk_bf16_f32 v51, v52, v53
	ds_write_b64 v220, v[50:51] offset:2048
	v_cvt_pk_bf16_f32 v54, v54, v55
	v_cvt_pk_bf16_f32 v55, v56, v57
	ds_write_b64 v220, v[54:55] offset:2560
	v_cvt_pk_bf16_f32 v58, v58, v59
	v_cvt_pk_bf16_f32 v59, v60, v61
	ds_write_b64 v220, v[58:59] offset:3072
	v_cvt_pk_bf16_f32 v62, v62, v63
	v_cvt_pk_bf16_f32 v63, v64, v65
	ds_write_b64 v220, v[62:63] offset:3584
	global_load_dwordx4 v[2:5], v209, s[70:71] nt
	global_load_dwordx4 v[6:9], v210, s[70:71] nt
	global_load_dwordx4 v[10:13], v211, s[70:71] nt
	global_load_dwordx4 v[14:17], v212, s[70:71] nt
	global_load_dwordx4 v[18:21], v213, s[70:71] nt
	global_load_dwordx4 v[22:25], v214, s[70:71] nt
	global_load_dwordx4 v[26:29], v215, s[70:71] nt
	global_load_dwordx4 v[30:33], v218, s[70:71] nt
	global_load_dwordx4 v[34:37], v209, s[72:73] nt
	global_load_dwordx4 v[38:41], v210, s[72:73] nt
	global_load_dwordx4 v[42:45], v211, s[72:73] nt
	global_load_dwordx4 v[46:49], v212, s[72:73] nt
	global_load_dwordx4 v[50:53], v213, s[72:73] nt
	global_load_dwordx4 v[54:57], v214, s[72:73] nt
	global_load_dwordx4 v[58:61], v215, s[72:73] nt
	global_load_dwordx4 v[62:65], v218, s[72:73] nt
	s_add_u32 s70, s70, 0x20000
	s_addc_u32 s71, s71, 0
	s_add_u32 s72, s72, 0x20000
	s_addc_u32 s73, s73, 0
	s_waitcnt lgkmcnt(0)
	s_barrier
; #define S2BAR() asm volatile("s_waitcnt lgkmcnt(0)\n\ts_barrier" ::: "memory")
;     ...
;         S2LOAD(kA, vA, 0); S2LOAD(kB, vB, 1);
;         S2WRITE(kA, vA, 0); S2LOAD(kA, vA, 2);
;         S2WRITE(kB, vB, 1); S2LOAD(kB, vB, 3);
;         S2BAR();
;         for (int i = 0; i < 60; i += 2) {
;             S2WRITE(kA, vA, i + 2); S2LOAD(kA, vA, i + 4); S2BAR();
;             S2WRITE(kB, vB, i + 3); S2LOAD(kB, vB, i + 5); S2BAR();
;         }
;         S2WRITE(kA, vA, 62);
	s_and_b32 s61, s60, 3
	s_lshl_b32 s61, s61, 15
	s_add_i32 s60, s60, 1
	v_add_u32_e32 v219, s61, v221
	v_add_u32_e32 v220, s61, v222
	s_waitcnt vmcnt(40)
	v_cvt_pk_bf16_f32 v66, v66, v67
	v_cvt_pk_bf16_f32 v67, v68, v69
	ds_write_b64 v219, v[66:67]
	v_cvt_pk_bf16_f32 v70, v70, v71
	v_cvt_pk_bf16_f32 v71, v72, v73
	ds_write_b64 v219, v[70:71] offset:128
	v_cvt_pk_bf16_f32 v74, v74, v75
	v_cvt_pk_bf16_f32 v75, v76, v77
	ds_write_b64 v219, v[74:75] offset:256
	v_cvt_pk_bf16_f32 v78, v78, v79
	v_cvt_pk_bf16_f32 v79, v80, v81
	ds_write_b64 v219, v[78:79] offset:384
	v_cvt_pk_bf16_f32 v82, v82, v83
	v_cvt_pk_bf16_f32 v83, v84, v85
	ds_write_b64 v219, v[82:83] offset:512
	v_cvt_pk_bf16_f32 v86, v86, v87
	v_cvt_pk_bf16_f32 v87, v88, v89
	ds_write_b64 v219, v[86:87] offset:640
	v_cvt_pk_bf16_f32 v90, v90, v91
	v_cvt_pk_bf16_f32 v91, v92, v93
	ds_write_b64 v219, v[90:91] offset:768
	v_cvt_pk_bf16_f32 v94, v94, v95
	v_cvt_pk_bf16_f32 v95, v96, v97
	ds_write_b64 v219, v[94:95] offset:896
	s_waitcnt vmcnt(32)
	v_cvt_pk_bf16_f32 v98, v98, v99
	v_cvt_pk_bf16_f32 v99, v100, v101
	ds_write_b64 v220, v[98:99]
	v_cvt_pk_bf16_f32 v102, v102, v103
	v_cvt_pk_bf16_f32 v103, v104, v105
	ds_write_b64 v220, v[102:103] offset:512
	v_cvt_pk_bf16_f32 v106, v106, v107
	v_cvt_pk_bf16_f32 v107, v108, v109
	ds_write_b64 v220, v[106:107] offset:1024
	v_cvt_pk_bf16_f32 v110, v110, v111
	v_cvt_pk_bf16_f32 v111, v112, v113
	ds_write_b64 v220, v[110:111] offset:1536
	v_cvt_pk_bf16_f32 v114, v114, v115
	v_cvt_pk_bf16_f32 v115, v116, v117
	ds_write_b64 v220, v[114:115] offset:2048
	v_cvt_pk_bf16_f32 v118, v118, v119
	v_cvt_pk_bf16_f32 v119, v120, v121
	ds_write_b64 v220, v[118:119] offset:2560
	v_cvt_pk_bf16_f32 v122, v122, v123
	v_cvt_pk_bf16_f32 v123, v124, v125
	ds_write_b64 v220, v[122:123] offset:3072
	v_cvt_pk_bf16_f32 v126, v126, v127
	v_cvt_pk_bf16_f32 v127, v128, v129
	ds_write_b64 v220, v[126:127] offset:3584
	global_load_dwordx4 v[66:69], v209, s[70:71] nt
	global_load_dwordx4 v[70:73], v210, s[70:71] nt
	global_load_dwordx4 v[74:77], v211, s[70:71] nt
	global_load_dwordx4 v[78:81], v212, s[70:71] nt
	global_load_dwordx4 v[82:85], v213, s[70:71] nt
	global_load_dwordx4 v[86:89], v214, s[70:71] nt
	global_load_dwordx4 v[90:93], v215, s[70:71] nt
	global_load_dwordx4 v[94:97], v218, s[70:71] nt
	global_load_dwordx4 v[98:101], v209, s[72:73] nt
	global_load_dwordx4 v[102:105], v210, s[72:73] nt
	global_load_dwordx4 v[106:109], v211, s[72:73] nt
	global_load_dwordx4 v[110:113], v212, s[72:73] nt
	global_load_dwordx4 v[114:117], v213, s[72:73] nt
	global_load_dwordx4 v[118:121], v214, s[72:73] nt
	global_load_dwordx4 v[122:125], v215, s[72:73] nt
	global_load_dwordx4 v[126:129], v218, s[72:73] nt
	s_add_u32 s70, s70, 0x20000
	s_addc_u32 s71, s71, 0
	s_add_u32 s72, s72, 0x20000
	s_addc_u32 s73, s73, 0
	s_waitcnt lgkmcnt(0)
	s_barrier
	s_add_i32 s62, s62, -1
	s_cmp_lg_u32 s62, 0
	s_cbranch_scc1 .Ls2ld_loop_0
	s_and_b32 s61, s60, 3
	s_lshl_b32 s61, s61, 15
	s_add_i32 s60, s60, 1
	v_add_u32_e32 v219, s61, v221
	v_add_u32_e32 v220, s61, v222
	s_waitcnt vmcnt(40)
	v_cvt_pk_bf16_f32 v130, v130, v131
	v_cvt_pk_bf16_f32 v131, v132, v133
	ds_write_b64 v219, v[130:131]
	v_cvt_pk_bf16_f32 v134, v134, v135
	v_cvt_pk_bf16_f32 v135, v136, v137
	ds_write_b64 v219, v[134:135] offset:128
	v_cvt_pk_bf16_f32 v144, v144, v145
	v_cvt_pk_bf16_f32 v145, v146, v147
	ds_write_b64 v219, v[144:145] offset:256
	v_cvt_pk_bf16_f32 v148, v148, v149
	v_cvt_pk_bf16_f32 v149, v150, v151
	ds_write_b64 v219, v[148:149] offset:384
	v_cvt_pk_bf16_f32 v152, v152, v153
	v_cvt_pk_bf16_f32 v153, v154, v155
	ds_write_b64 v219, v[152:153] offset:512
	v_cvt_pk_bf16_f32 v156, v156, v157
	v_cvt_pk_bf16_f32 v157, v158, v159
	ds_write_b64 v219, v[156:157] offset:640
	v_cvt_pk_bf16_f32 v160, v160, v161
	v_cvt_pk_bf16_f32 v161, v162, v163
	ds_write_b64 v219, v[160:161] offset:768
	v_cvt_pk_bf16_f32 v164, v164, v165
	v_cvt_pk_bf16_f32 v165, v166, v167
	ds_write_b64 v219, v[164:165] offset:896
	s_waitcnt vmcnt(32)
	v_cvt_pk_bf16_f32 v168, v168, v169
	v_cvt_pk_bf16_f32 v169, v170, v171
	ds_write_b64 v220, v[168:169]
	v_cvt_pk_bf16_f32 v172, v172, v173
	v_cvt_pk_bf16_f32 v173, v174, v175
	ds_write_b64 v220, v[172:173] offset:512
	v_cvt_pk_bf16_f32 v176, v176, v177
	v_cvt_pk_bf16_f32 v177, v178, v179
	ds_write_b64 v220, v[176:177] offset:1024
	v_cvt_pk_bf16_f32 v180, v180, v181
	v_cvt_pk_bf16_f32 v181, v182, v183
	ds_write_b64 v220, v[180:181] offset:1536
	v_cvt_pk_bf16_f32 v184, v184, v185
	v_cvt_pk_bf16_f32 v185, v186, v187
	ds_write_b64 v220, v[184:185] offset:2048
	v_cvt_pk_bf16_f32 v188, v188, v189
	v_cvt_pk_bf16_f32 v189, v190, v191
	ds_write_b64 v220, v[188:189] offset:2560
	v_cvt_pk_bf16_f32 v192, v192, v193
	v_cvt_pk_bf16_f32 v193, v194, v195
	ds_write_b64 v220, v[192:193] offset:3072
	v_cvt_pk_bf16_f32 v196, v196, v197
	v_cvt_pk_bf16_f32 v197, v198, v199
	ds_write_b64 v220, v[196:197] offset:3584
	global_load_dwordx4 v[130:133], v209, s[70:71] nt
	global_load_dwordx4 v[134:137], v210, s[70:71] nt
	global_load_dwordx4 v[144:147], v211, s[70:71] nt
	global_load_dwordx4 v[148:151], v212, s[70:71] nt
	global_load_dwordx4 v[152:155], v213, s[70:71] nt
	global_load_dwordx4 v[156:159], v214, s[70:71] nt
	global_load_dwordx4 v[160:163], v215, s[70:71] nt
	global_load_dwordx4 v[164:167], v218, s[70:71] nt
	global_load_dwordx4 v[168:171], v209, s[72:73] nt
	global_load_dwordx4 v[172:175], v210, s[72:73] nt
	global_load_dwordx4 v[176:179], v211, s[72:73] nt
	global_load_dwordx4 v[180:183], v212, s[72:73] nt
	global_load_dwordx4 v[184:187], v213, s[72:73] nt
	global_load_dwordx4 v[188:191], v214, s[72:73] nt
	global_load_dwordx4 v[192:195], v215, s[72:73] nt
	global_load_dwordx4 v[196:199], v218, s[72:73] nt
	s_add_u32 s70, s70, 0x20000
	s_addc_u32 s71, s71, 0
	s_add_u32 s72, s72, 0x20000
	s_addc_u32 s73, s73, 0
	s_waitcnt lgkmcnt(0)
	s_barrier
; #define S2BAR() asm volatile("s_waitcnt lgkmcnt(0)\n\ts_barrier" ::: "memory")
;     ...
;         S2LOAD(kA, vA, 0); S2LOAD(kB, vB, 1);
;         S2WRITE(kA, vA, 0); S2LOAD(kA, vA, 2);
;         S2WRITE(kB, vB, 1); S2LOAD(kB, vB, 3);
;         S2BAR();
;         for (int i = 0; i < 60; i += 2) {
;             S2WRITE(kA, vA, i + 2); S2LOAD(kA, vA, i + 4); S2BAR();
;             S2WRITE(kB, vB, i + 3); S2LOAD(kB, vB, i + 5); S2BAR();
;         }
;         S2WRITE(kA, vA, 62);
	s_and_b32 s61, s60, 3
	s_lshl_b32 s61, s61, 15
	s_add_i32 s60, s60, 1
	v_add_u32_e32 v219, s61, v221
	v_add_u32_e32 v220, s61, v222
	s_waitcnt vmcnt(40)
	v_cvt_pk_bf16_f32 v2, v2, v3
	v_cvt_pk_bf16_f32 v3, v4, v5
	ds_write_b64 v219, v[2:3]
	v_cvt_pk_bf16_f32 v6, v6, v7
	v_cvt_pk_bf16_f32 v7, v8, v9
	ds_write_b64 v219, v[6:7] offset:128
	v_cvt_pk_bf16_f32 v10, v10, v11
	v_cvt_pk_bf16_f32 v11, v12, v13
	ds_write_b64 v219, v[10:11] offset:256
	v_cvt_pk_bf16_f32 v14, v14, v15
	v_cvt_pk_bf16_f32 v15, v16, v17
	ds_write_b64 v219, v[14:15] offset:384
	v_cvt_pk_bf16_f32 v18, v18, v19
	v_cvt_pk_bf16_f32 v19, v20, v21
	ds_write_b64 v219, v[18:19] offset:512
	v_cvt_pk_bf16_f32 v22, v22, v23
	v_cvt_pk_bf16_f32 v23, v24, v25
	ds_write_b64 v219, v[22:23] offset:640
	v_cvt_pk_bf16_f32 v26, v26, v27
	v_cvt_pk_bf16_f32 v27, v28, v29
	ds_write_b64 v219, v[26:27] offset:768
	v_cvt_pk_bf16_f32 v30, v30, v31
	v_cvt_pk_bf16_f32 v31, v32, v33
	ds_write_b64 v219, v[30:31] offset:896
	s_waitcnt vmcnt(32)
	v_cvt_pk_bf16_f32 v34, v34, v35
	v_cvt_pk_bf16_f32 v35, v36, v37
	ds_write_b64 v220, v[34:35]
	v_cvt_pk_bf16_f32 v38, v38, v39
	v_cvt_pk_bf16_f32 v39, v40, v41
	ds_write_b64 v220, v[38:39] offset:512
	v_cvt_pk_bf16_f32 v42, v42, v43
	v_cvt_pk_bf16_f32 v43, v44, v45
	ds_write_b64 v220, v[42:43] offset:1024
	v_cvt_pk_bf16_f32 v46, v46, v47
	v_cvt_pk_bf16_f32 v47, v48, v49
	ds_write_b64 v220, v[46:47] offset:1536
	v_cvt_pk_bf16_f32 v50, v50, v51
	v_cvt_pk_bf16_f32 v51, v52, v53
	ds_write_b64 v220, v[50:51] offset:2048
	v_cvt_pk_bf16_f32 v54, v54, v55
	v_cvt_pk_bf16_f32 v55, v56, v57
	ds_write_b64 v220, v[54:55] offset:2560
	v_cvt_pk_bf16_f32 v58, v58, v59
	v_cvt_pk_bf16_f32 v59, v60, v61
	ds_write_b64 v220, v[58:59] offset:3072
	v_cvt_pk_bf16_f32 v62, v62, v63
	v_cvt_pk_bf16_f32 v63, v64, v65
	ds_write_b64 v220, v[62:63] offset:3584
	global_load_dwordx4 v[2:5], v209, s[70:71] nt
	global_load_dwordx4 v[6:9], v210, s[70:71] nt
	global_load_dwordx4 v[10:13], v211, s[70:71] nt
	global_load_dwordx4 v[14:17], v212, s[70:71] nt
	global_load_dwordx4 v[18:21], v213, s[70:71] nt
	global_load_dwordx4 v[22:25], v214, s[70:71] nt
	global_load_dwordx4 v[26:29], v215, s[70:71] nt
	global_load_dwordx4 v[30:33], v218, s[70:71] nt
	global_load_dwordx4 v[34:37], v209, s[72:73] nt
	global_load_dwordx4 v[38:41], v210, s[72:73] nt
	global_load_dwordx4 v[42:45], v211, s[72:73] nt
	global_load_dwordx4 v[46:49], v212, s[72:73] nt
	global_load_dwordx4 v[50:53], v213, s[72:73] nt
	global_load_dwordx4 v[54:57], v214, s[72:73] nt
	global_load_dwordx4 v[58:61], v215, s[72:73] nt
	global_load_dwordx4 v[62:65], v218, s[72:73] nt
	s_add_u32 s70, s70, 0x20000
	s_addc_u32 s71, s71, 0
	s_add_u32 s72, s72, 0x20000
	s_addc_u32 s73, s73, 0
	s_waitcnt lgkmcnt(0)
	s_barrier
	s_and_b32 s61, s60, 3
	s_lshl_b32 s61, s61, 15
	s_add_i32 s60, s60, 1
	v_add_u32_e32 v219, s61, v221
	v_add_u32_e32 v220, s61, v222
	s_waitcnt vmcnt(40)
	v_cvt_pk_bf16_f32 v66, v66, v67
	v_cvt_pk_bf16_f32 v67, v68, v69
	ds_write_b64 v219, v[66:67]
	v_cvt_pk_bf16_f32 v70, v70, v71
	v_cvt_pk_bf16_f32 v71, v72, v73
	ds_write_b64 v219, v[70:71] offset:128
	v_cvt_pk_bf16_f32 v74, v74, v75
	v_cvt_pk_bf16_f32 v75, v76, v77
	ds_write_b64 v219, v[74:75] offset:256
	v_cvt_pk_bf16_f32 v78, v78, v79
	v_cvt_pk_bf16_f32 v79, v80, v81
	ds_write_b64 v219, v[78:79] offset:384
	v_cvt_pk_bf16_f32 v82, v82, v83
	v_cvt_pk_bf16_f32 v83, v84, v85
	ds_write_b64 v219, v[82:83] offset:512
	v_cvt_pk_bf16_f32 v86, v86, v87
	v_cvt_pk_bf16_f32 v87, v88, v89
	ds_write_b64 v219, v[86:87] offset:640
	v_cvt_pk_bf16_f32 v90, v90, v91
	v_cvt_pk_bf16_f32 v91, v92, v93
	ds_write_b64 v219, v[90:91] offset:768
	v_cvt_pk_bf16_f32 v94, v94, v95
	v_cvt_pk_bf16_f32 v95, v96, v97
	ds_write_b64 v219, v[94:95] offset:896
	s_waitcnt vmcnt(32)
	v_cvt_pk_bf16_f32 v98, v98, v99
	v_cvt_pk_bf16_f32 v99, v100, v101
	ds_write_b64 v220, v[98:99]
	v_cvt_pk_bf16_f32 v102, v102, v103
	v_cvt_pk_bf16_f32 v103, v104, v105
	ds_write_b64 v220, v[102:103] offset:512
	v_cvt_pk_bf16_f32 v106, v106, v107
	v_cvt_pk_bf16_f32 v107, v108, v109
	ds_write_b64 v220, v[106:107] offset:1024
	v_cvt_pk_bf16_f32 v110, v110, v111
	v_cvt_pk_bf16_f32 v111, v112, v113
	ds_write_b64 v220, v[110:111] offset:1536
	v_cvt_pk_bf16_f32 v114, v114, v115
	v_cvt_pk_bf16_f32 v115, v116, v117
	ds_write_b64 v220, v[114:115] offset:2048
	v_cvt_pk_bf16_f32 v118, v118, v119
	v_cvt_pk_bf16_f32 v119, v120, v121
	ds_write_b64 v220, v[118:119] offset:2560
	v_cvt_pk_bf16_f32 v122, v122, v123
	v_cvt_pk_bf16_f32 v123, v124, v125
	ds_write_b64 v220, v[122:123] offset:3072
	v_cvt_pk_bf16_f32 v126, v126, v127
	v_cvt_pk_bf16_f32 v127, v128, v129
	ds_write_b64 v220, v[126:127] offset:3584
	s_waitcnt lgkmcnt(0)
	s_barrier
; #define LAS __attribute__((address_space(3)))
; #define S2BAR() asm volatile("s_waitcnt lgkmcnt(0)\n\ts_barrier" ::: "memory")
;     ...
;         S2WRITE(kA, vA, 62);
;         {
;             const int keyn = lt >> 4, cc = lt & 15;
; #pragma unroll
;             for (int i2 = 0; i2 < 4; ++i2) { const size_t krow = (size_t)(NP + b * 64 + keyn + 16 * i2);
;                 kA[i2] = *(const v4u*)(C.DK + krow * 512 + h * 128 + cc * 8); vA[i2] = *(const v4u*)(C.DV + krow * 512 + h * 128 + cc * 8); }
;             S2BAR();
;             S2WRITE(kB, vB, 63); S2BAR();
; #pragma unroll
;             for (int i2 = 0; i2 < 4; ++i2) { const int key = keyn + 16 * i2;
;                 *(LAS v4u*)(lds + (cc >> 3) * 8192 + (cc & 7) * 1024 + ((key ^ (cc & 7)) & 63) * 16) = kA[i2];
;                 *(LAS v4u*)(lds + S2_V + (cc >> 2) * 4096 + (key >> 4) * 1024 + (key & 15) * 64 + (cc & 3) * 16) = vA[i2]; }
;             S2BAR();
;         }
;         S2BAR(); S2BAR();
	s_and_b32 s61, s60, 3
	s_lshl_b32 s61, s61, 15
	s_add_i32 s60, s60, 1
	v_add_u32_e32 v219, s61, v221
	v_add_u32_e32 v220, s61, v222
	s_waitcnt vmcnt(24)
	v_cvt_pk_bf16_f32 v130, v130, v131
	v_cvt_pk_bf16_f32 v131, v132, v133
	ds_write_b64 v219, v[130:131]
	v_cvt_pk_bf16_f32 v134, v134, v135
	v_cvt_pk_bf16_f32 v135, v136, v137
	ds_write_b64 v219, v[134:135] offset:128
	v_cvt_pk_bf16_f32 v144, v144, v145
	v_cvt_pk_bf16_f32 v145, v146, v147
	ds_write_b64 v219, v[144:145] offset:256
	v_cvt_pk_bf16_f32 v148, v148, v149
	v_cvt_pk_bf16_f32 v149, v150, v151
	ds_write_b64 v219, v[148:149] offset:384
	v_cvt_pk_bf16_f32 v152, v152, v153
	v_cvt_pk_bf16_f32 v153, v154, v155
	ds_write_b64 v219, v[152:153] offset:512
	v_cvt_pk_bf16_f32 v156, v156, v157
	v_cvt_pk_bf16_f32 v157, v158, v159
	ds_write_b64 v219, v[156:157] offset:640
	v_cvt_pk_bf16_f32 v160, v160, v161
	v_cvt_pk_bf16_f32 v161, v162, v163
	ds_write_b64 v219, v[160:161] offset:768
	v_cvt_pk_bf16_f32 v164, v164, v165
	v_cvt_pk_bf16_f32 v165, v166, v167
	ds_write_b64 v219, v[164:165] offset:896
	s_waitcnt vmcnt(16)
	v_cvt_pk_bf16_f32 v168, v168, v169
	v_cvt_pk_bf16_f32 v169, v170, v171
	ds_write_b64 v220, v[168:169]
	v_cvt_pk_bf16_f32 v172, v172, v173
	v_cvt_pk_bf16_f32 v173, v174, v175
	ds_write_b64 v220, v[172:173] offset:512
	v_cvt_pk_bf16_f32 v176, v176, v177
	v_cvt_pk_bf16_f32 v177, v178, v179
	ds_write_b64 v220, v[176:177] offset:1024
	v_cvt_pk_bf16_f32 v180, v180, v181
	v_cvt_pk_bf16_f32 v181, v182, v183
	ds_write_b64 v220, v[180:181] offset:1536
	v_cvt_pk_bf16_f32 v184, v184, v185
	v_cvt_pk_bf16_f32 v185, v186, v187
	ds_write_b64 v220, v[184:185] offset:2048
	v_cvt_pk_bf16_f32 v188, v188, v189
	v_cvt_pk_bf16_f32 v189, v190, v191
	ds_write_b64 v220, v[188:189] offset:2560
	v_cvt_pk_bf16_f32 v192, v192, v193
	v_cvt_pk_bf16_f32 v193, v194, v195
	ds_write_b64 v220, v[192:193] offset:3072
	v_cvt_pk_bf16_f32 v196, v196, v197
	v_cvt_pk_bf16_f32 v197, v198, v199
	ds_write_b64 v220, v[196:197] offset:3584
	v_lshrrev_b32_e32 v224, 4, v223
	v_and_b32_e32 v225, 15, v223
	v_readlane_b32 s12, v253, 56
	v_readlane_b32 s13, v253, 57
	v_readlane_b32 s14, v253, 58
	v_readlane_b32 s15, v253, 59
	s_lshl_b32 s6, s2, 6
	s_add_i32 s6, s6, 0x4000
	s_lshl_b32 s6, s6, 10
	s_lshl_b32 s61, s3, 8
	s_add_i32 s6, s6, s61
	s_add_u32 s12, s12, s6
	s_addc_u32 s13, s13, 0
	s_add_u32 s14, s14, s6
	s_addc_u32 s15, s15, 0
	v_lshlrev_b32_e32 v138, 10, v224
	v_lshl_or_b32 v138, v225, 4, v138
	global_load_dwordx4 v[144:147], v138, s[12:13]
	global_load_dwordx4 v[160:163], v138, s[14:15]
	v_add_u32_e32 v138, 0x4000, v138
	global_load_dwordx4 v[148:151], v138, s[12:13]
	global_load_dwordx4 v[164:167], v138, s[14:15]
	v_add_u32_e32 v138, 0x4000, v138
	global_load_dwordx4 v[152:155], v138, s[12:13]
	global_load_dwordx4 v[168:171], v138, s[14:15]
	v_add_u32_e32 v138, 0x4000, v138
	global_load_dwordx4 v[156:159], v138, s[12:13]
	global_load_dwordx4 v[172:175], v138, s[14:15]
	s_waitcnt lgkmcnt(0)
	s_barrier
	s_and_b32 s61, s60, 3
	s_lshl_b32 s61, s61, 15
	s_add_i32 s60, s60, 1
	v_add_u32_e32 v219, s61, v221
	v_add_u32_e32 v220, s61, v222
	s_waitcnt vmcnt(16)
	v_cvt_pk_bf16_f32 v2, v2, v3
	v_cvt_pk_bf16_f32 v3, v4, v5
	ds_write_b64 v219, v[2:3]
	v_cvt_pk_bf16_f32 v6, v6, v7
	v_cvt_pk_bf16_f32 v7, v8, v9
	ds_write_b64 v219, v[6:7] offset:128
	v_cvt_pk_bf16_f32 v10, v10, v11
	v_cvt_pk_bf16_f32 v11, v12, v13
	ds_write_b64 v219, v[10:11] offset:256
	v_cvt_pk_bf16_f32 v14, v14, v15
	v_cvt_pk_bf16_f32 v15, v16, v17
	ds_write_b64 v219, v[14:15] offset:384
	v_cvt_pk_bf16_f32 v18, v18, v19
	v_cvt_pk_bf16_f32 v19, v20, v21
	ds_write_b64 v219, v[18:19] offset:512
	v_cvt_pk_bf16_f32 v22, v22, v23
	v_cvt_pk_bf16_f32 v23, v24, v25
	ds_write_b64 v219, v[22:23] offset:640
	v_cvt_pk_bf16_f32 v26, v26, v27
	v_cvt_pk_bf16_f32 v27, v28, v29
	ds_write_b64 v219, v[26:27] offset:768
	v_cvt_pk_bf16_f32 v30, v30, v31
	v_cvt_pk_bf16_f32 v31, v32, v33
	ds_write_b64 v219, v[30:31] offset:896
	s_waitcnt vmcnt(8)
	v_cvt_pk_bf16_f32 v34, v34, v35
	v_cvt_pk_bf16_f32 v35, v36, v37
	ds_write_b64 v220, v[34:35]
	v_cvt_pk_bf16_f32 v38, v38, v39
	v_cvt_pk_bf16_f32 v39, v40, v41
	ds_write_b64 v220, v[38:39] offset:512
	v_cvt_pk_bf16_f32 v42, v42, v43
	v_cvt_pk_bf16_f32 v43, v44, v45
	ds_write_b64 v220, v[42:43] offset:1024
	v_cvt_pk_bf16_f32 v46, v46, v47
	v_cvt_pk_bf16_f32 v47, v48, v49
	ds_write_b64 v220, v[46:47] offset:1536
	v_cvt_pk_bf16_f32 v50, v50, v51
	v_cvt_pk_bf16_f32 v51, v52, v53
	ds_write_b64 v220, v[50:51] offset:2048
	v_cvt_pk_bf16_f32 v54, v54, v55
	v_cvt_pk_bf16_f32 v55, v56, v57
	ds_write_b64 v220, v[54:55] offset:2560
	v_cvt_pk_bf16_f32 v58, v58, v59
	v_cvt_pk_bf16_f32 v59, v60, v61
	ds_write_b64 v220, v[58:59] offset:3072
	v_cvt_pk_bf16_f32 v62, v62, v63
	v_cvt_pk_bf16_f32 v63, v64, v65
	ds_write_b64 v220, v[62:63] offset:3584
	s_waitcnt lgkmcnt(0)
	s_barrier
	v_lshrrev_b32_e32 v139, 3, v225
	v_lshlrev_b32_e32 v139, 13, v139
	v_and_b32_e32 v202, 7, v225
	v_lshl_or_b32 v139, v202, 10, v139
	v_lshrrev_b32_e32 v143, 2, v225
	v_lshlrev_b32_e32 v143, 12, v143
	v_and_b32_e32 v203, 3, v225
	v_lshl_or_b32 v143, v203, 4, v143
	v_lshl_or_b32 v143, v224, 6, v143
	v_add_u32_e32 v143, 0x4000, v143
	s_waitcnt vmcnt(0)
	v_xor_b32_e32 v219, v224, v202
	v_and_b32_e32 v219, 63, v219
	v_lshl_or_b32 v219, v219, 4, v139
	ds_write_b128 v219, v[144:147]
	ds_write_b128 v143, v[160:163]
	ds_write_b128 v219, v[148:151] offset:256
	ds_write_b128 v143, v[164:167] offset:1024
	ds_write_b128 v219, v[152:155] offset:512
	ds_write_b128 v143, v[168:171] offset:2048
	ds_write_b128 v219, v[156:159] offset:768
	ds_write_b128 v143, v[172:175] offset:3072
	s_waitcnt lgkmcnt(0)
	s_barrier
	s_waitcnt lgkmcnt(0)
	s_barrier
	s_waitcnt lgkmcnt(0)
	s_barrier
	s_mov_b64 s[2:3], 0

;     ...
;         const int lt = tid - 256;
;         const int key0 = lt >> 5, q16 = lt & 31, cch = q16 >> 1, hlf = q16 & 1;
;         const char* kg = (const char*)(C.cdk + ((size_t)b * PAST * 4 + h) * 128) + (size_t)key0 * 2048 + q16 * 16;
;         const char* vg = (const char*)(C.cdv + ((size_t)b * PAST * 4 + h) * 128) + (size_t)key0 * 2048 + q16 * 16;
;         const int kd0 = (cch >> 3) * 8192 + (cch & 7) * 1024 + ((key0 ^ (cch & 7)) & 63) * 16 + hlf * 8;
;         const int vd0 = S2_V + (cch >> 2) * 4096 + key0 * 64 + (cch & 3) * 16 + hlf * 8;
;         v4u kA[8], vA[8], kB[8], vB[8];
;     ...
;         S2LOAD(kA, vA, 0); S2LOAD(kB, vB, 1);
;         S2WRITE(kA, vA, 0); S2LOAD(kA, vA, 2);
;         S2WRITE(kB, vB, 1); S2LOAD(kB, vB, 3);
.LBB0_656:
	s_or_b64 exec, exec, s[2:3]
	s_waitcnt lgkmcnt(0)
	s_barrier
	ds_read_b32 v2, v1
	s_movk_i32 s2, 0x7f
	s_waitcnt lgkmcnt(0)
	v_cmp_lt_u32_e32 vcc, s2, v2
	s_mov_b64 s[2:3], -1
	s_cbranch_vccnz .LBB0_651
	v_mov_b32_e32 v140, v0
	v_and_b32_e32 v142, 3, v2
	v_readfirstlane_b32 s5, v140
	s_ashr_i32 s4, s5, 6
	s_cmp_lt_i32 s4, 4
	v_and_b32_e32 v208, 31, v140
	v_lshrrev_b32_e32 v207, 2, v2
	s_cselect_b64 s[10:11], -1, 0
	s_cmp_gt_i32 s4, 3
	v_lshlrev_b32_e32 v206, 7, v142
	v_lshlrev_b32_e32 v141, 3, v140
	s_barrier
	s_cbranch_scc0 .LBB0_661
	v_add_u32_e32 v223, 0xffffff00, v140
	v_lshrrev_b32_e32 v224, 5, v223
	v_and_b32_e32 v225, 31, v223
	v_lshlrev_b32_e32 v209, 11, v224
	v_lshl_or_b32 v209, v225, 4, v209
	v_add_u32_e32 v210, 0x4000, v209
	v_add_u32_e32 v211, 0x8000, v209
	v_add_u32_e32 v212, 0xc000, v209
	v_add_u32_e32 v213, 0x10000, v209
	v_add_u32_e32 v214, 0x14000, v209
	v_add_u32_e32 v215, 0x18000, v209
	v_add_u32_e32 v218, 0x1c000, v209
	v_lshrrev_b32_e32 v138, 1, v225
	v_and_b32_e32 v139, 1, v225
	v_lshlrev_b32_e32 v139, 3, v139
	v_lshrrev_b32_e32 v143, 3, v138
	v_lshlrev_b32_e32 v143, 13, v143
	v_and_b32_e32 v202, 7, v138
	v_lshl_or_b32 v143, v202, 10, v143
	v_xor_b32_e32 v203, v224, v202
	v_and_b32_e32 v203, 63, v203
	v_lshl_or_b32 v143, v203, 4, v143
	v_or_b32_e32 v221, v143, v139
	v_lshrrev_b32_e32 v143, 2, v138
	v_lshlrev_b32_e32 v143, 12, v143
	v_lshl_or_b32 v143, v224, 6, v143
	v_and_b32_e32 v202, 3, v138
	v_lshl_or_b32 v143, v202, 4, v143
	v_or_b32_e32 v143, v143, v139
	v_add_u32_e32 v222, 0x4000, v143
	v_readfirstlane_b32 s2, v207
	v_readfirstlane_b32 s3, v142
	v_readlane_b32 s70, v253, 17
	v_readlane_b32 s71, v253, 18
	v_readlane_b32 s72, v253, 19
	v_readlane_b32 s73, v253, 20
	s_lshl_b32 s6, s2, 23
	s_lshl_b32 s12, s3, 9
	s_add_i32 s6, s6, s12
	s_add_u32 s70, s70, s6
	s_addc_u32 s71, s71, 0
	s_add_u32 s72, s72, s6
	s_addc_u32 s73, s73, 0
	s_mov_b32 s60, 0
	global_load_dwordx4 v[2:5], v209, s[70:71] nt
	global_load_dwordx4 v[6:9], v210, s[70:71] nt
	global_load_dwordx4 v[10:13], v211, s[70:71] nt
	global_load_dwordx4 v[14:17], v212, s[70:71] nt
	global_load_dwordx4 v[18:21], v213, s[70:71] nt
	global_load_dwordx4 v[22:25], v214, s[70:71] nt
	global_load_dwordx4 v[26:29], v215, s[70:71] nt
	global_load_dwordx4 v[30:33], v218, s[70:71] nt
	global_load_dwordx4 v[34:37], v209, s[72:73] nt
	global_load_dwordx4 v[38:41], v210, s[72:73] nt
	global_load_dwordx4 v[42:45], v211, s[72:73] nt
	global_load_dwordx4 v[46:49], v212, s[72:73] nt
	global_load_dwordx4 v[50:53], v213, s[72:73] nt
	global_load_dwordx4 v[54:57], v214, s[72:73] nt
	global_load_dwordx4 v[58:61], v215, s[72:73] nt
	global_load_dwordx4 v[62:65], v218, s[72:73] nt
	s_add_u32 s70, s70, 0x20000
	s_addc_u32 s71, s71, 0
	s_add_u32 s72, s72, 0x20000
	s_addc_u32 s73, s73, 0
	global_load_dwordx4 v[66:69], v209, s[70:71] nt
	global_load_dwordx4 v[70:73], v210, s[70:71] nt
	global_load_dwordx4 v[74:77], v211, s[70:71] nt
	global_load_dwordx4 v[78:81], v212, s[70:71] nt
	global_load_dwordx4 v[82:85], v213, s[70:71] nt
	global_load_dwordx4 v[86:89], v214, s[70:71] nt
	global_load_dwordx4 v[90:93], v215, s[70:71] nt
	global_load_dwordx4 v[94:97], v218, s[70:71] nt
	global_load_dwordx4 v[98:101], v209, s[72:73] nt
	global_load_dwordx4 v[102:105], v210, s[72:73] nt
	global_load_dwordx4 v[106:109], v211, s[72:73] nt
	global_load_dwordx4 v[110:113], v212, s[72:73] nt
	global_load_dwordx4 v[114:117], v213, s[72:73] nt
	global_load_dwordx4 v[118:121], v214, s[72:73] nt
	global_load_dwordx4 v[122:125], v215, s[72:73] nt
	global_load_dwordx4 v[126:129], v218, s[72:73] nt
	s_add_u32 s70, s70, 0x20000
	s_addc_u32 s71, s71, 0
	s_add_u32 s72, s72, 0x20000
	s_addc_u32 s73, s73, 0
	global_load_dwordx4 v[130:133], v209, s[70:71] nt
	global_load_dwordx4 v[134:137], v210, s[70:71] nt
	global_load_dwordx4 v[144:147], v211, s[70:71] nt
	global_load_dwordx4 v[148:151], v212, s[70:71] nt
	global_load_dwordx4 v[152:155], v213, s[70:71] nt
	global_load_dwordx4 v[156:159], v214, s[70:71] nt
	global_load_dwordx4 v[160:163], v215, s[70:71] nt
	global_load_dwordx4 v[164:167], v218, s[70:71] nt
	global_load_dwordx4 v[168:171], v209, s[72:73] nt
	global_load_dwordx4 v[172:175], v210, s[72:73] nt
	global_load_dwordx4 v[176:179], v211, s[72:73] nt
	global_load_dwordx4 v[180:183], v212, s[72:73] nt
	global_load_dwordx4 v[184:187], v213, s[72:73] nt
	global_load_dwordx4 v[188:191], v214, s[72:73] nt
	global_load_dwordx4 v[192:195], v215, s[72:73] nt
	global_load_dwordx4 v[196:199], v218, s[72:73] nt
	s_add_u32 s70, s70, 0x20000
	s_addc_u32 s71, s71, 0
	s_add_u32 s72, s72, 0x20000
	s_addc_u32 s73, s73, 0
	s_and_b32 s61, s60, 3
	s_lshl_b32 s61, s61, 15
	s_add_i32 s60, s60, 1
	v_add_u32_e32 v219, s61, v221
	v_add_u32_e32 v220, s61, v222
	s_waitcnt vmcnt(40)
; #define S2BAR() asm volatile("s_waitcnt lgkmcnt(0)\n\ts_barrier" ::: "memory")
;     ...
;         S2LOAD(kA, vA, 0); S2LOAD(kB, vB, 1);
;         S2WRITE(kA, vA, 0); S2LOAD(kA, vA, 2);
;         S2WRITE(kB, vB, 1); S2LOAD(kB, vB, 3);
;         S2BAR();
	v_cvt_pk_bf16_f32 v2, v2, v3
	v_cvt_pk_bf16_f32 v3, v4, v5
	ds_write_b64 v219, v[2:3]
	v_cvt_pk_bf16_f32 v6, v6, v7
	v_cvt_pk_bf16_f32 v7, v8, v9
	ds_write_b64 v219, v[6:7] offset:128
	v_cvt_pk_bf16_f32 v10, v10, v11
	v_cvt_pk_bf16_f32 v11, v12, v13
	ds_write_b64 v219, v[10:11] offset:256
	v_cvt_pk_bf16_f32 v14, v14, v15
	v_cvt_pk_bf16_f32 v15, v16, v17
	ds_write_b64 v219, v[14:15] offset:384
	v_cvt_pk_bf16_f32 v18, v18, v19
	v_cvt_pk_bf16_f32 v19, v20, v21
	ds_write_b64 v219, v[18:19] offset:512
	v_cvt_pk_bf16_f32 v22, v22, v23
	v_cvt_pk_bf16_f32 v23, v24, v25
	ds_write_b64 v219, v[22:23] offset:640
	v_cvt_pk_bf16_f32 v26, v26, v27
	v_cvt_pk_bf16_f32 v27, v28, v29
	ds_write_b64 v219, v[26:27] offset:768
	v_cvt_pk_bf16_f32 v30, v30, v31
	v_cvt_pk_bf16_f32 v31, v32, v33
	ds_write_b64 v219, v[30:31] offset:896
	s_waitcnt vmcnt(32)
	v_cvt_pk_bf16_f32 v34, v34, v35
	v_cvt_pk_bf16_f32 v35, v36, v37
	ds_write_b64 v220, v[34:35]
	v_cvt_pk_bf16_f32 v38, v38, v39
	v_cvt_pk_bf16_f32 v39, v40, v41
	ds_write_b64 v220, v[38:39] offset:512
	v_cvt_pk_bf16_f32 v42, v42, v43
	v_cvt_pk_bf16_f32 v43, v44, v45
	ds_write_b64 v220, v[42:43] offset:1024
	v_cvt_pk_bf16_f32 v46, v46, v47
	v_cvt_pk_bf16_f32 v47, v48, v49
	ds_write_b64 v220, v[46:47] offset:1536
	v_cvt_pk_bf16_f32 v50, v50, v51
	v_cvt_pk_bf16_f32 v51, v52, v53
	ds_write_b64 v220, v[50:51] offset:2048
	v_cvt_pk_bf16_f32 v54, v54, v55
	v_cvt_pk_bf16_f32 v55, v56, v57
	ds_write_b64 v220, v[54:55] offset:2560
	v_cvt_pk_bf16_f32 v58, v58, v59
	v_cvt_pk_bf16_f32 v59, v60, v61
	ds_write_b64 v220, v[58:59] offset:3072
	v_cvt_pk_bf16_f32 v62, v62, v63
	v_cvt_pk_bf16_f32 v63, v64, v65
	ds_write_b64 v220, v[62:63] offset:3584
	global_load_dwordx4 v[2:5], v209, s[70:71] nt
	global_load_dwordx4 v[6:9], v210, s[70:71] nt
	global_load_dwordx4 v[10:13], v211, s[70:71] nt
	global_load_dwordx4 v[14:17], v212, s[70:71] nt
	global_load_dwordx4 v[18:21], v213, s[70:71] nt
	global_load_dwordx4 v[22:25], v214, s[70:71] nt
	global_load_dwordx4 v[26:29], v215, s[70:71] nt
	global_load_dwordx4 v[30:33], v218, s[70:71] nt
	global_load_dwordx4 v[34:37], v209, s[72:73] nt
	global_load_dwordx4 v[38:41], v210, s[72:73] nt
	global_load_dwordx4 v[42:45], v211, s[72:73] nt
	global_load_dwordx4 v[46:49], v212, s[72:73] nt
	global_load_dwordx4 v[50:53], v213, s[72:73] nt
	global_load_dwordx4 v[54:57], v214, s[72:73] nt
	global_load_dwordx4 v[58:61], v215, s[72:73] nt
	global_load_dwordx4 v[62:65], v218, s[72:73] nt
	s_add_u32 s70, s70, 0x20000
	s_addc_u32 s71, s71, 0
	s_add_u32 s72, s72, 0x20000
	s_addc_u32 s73, s73, 0
	s_and_b32 s61, s60, 3
	s_lshl_b32 s61, s61, 15
	s_add_i32 s60, s60, 1
	v_add_u32_e32 v219, s61, v221
	v_add_u32_e32 v220, s61, v222
	s_waitcnt vmcnt(40)
	v_cvt_pk_bf16_f32 v66, v66, v67
	v_cvt_pk_bf16_f32 v67, v68, v69
	ds_write_b64 v219, v[66:67]
	v_cvt_pk_bf16_f32 v70, v70, v71
	v_cvt_pk_bf16_f32 v71, v72, v73
	ds_write_b64 v219, v[70:71] offset:128
	v_cvt_pk_bf16_f32 v74, v74, v75
	v_cvt_pk_bf16_f32 v75, v76, v77
	ds_write_b64 v219, v[74:75] offset:256
	v_cvt_pk_bf16_f32 v78, v78, v79
	v_cvt_pk_bf16_f32 v79, v80, v81
	ds_write_b64 v219, v[78:79] offset:384
	v_cvt_pk_bf16_f32 v82, v82, v83
	v_cvt_pk_bf16_f32 v83, v84, v85
	ds_write_b64 v219, v[82:83] offset:512
	v_cvt_pk_bf16_f32 v86, v86, v87
	v_cvt_pk_bf16_f32 v87, v88, v89
	ds_write_b64 v219, v[86:87] offset:640
	v_cvt_pk_bf16_f32 v90, v90, v91
	v_cvt_pk_bf16_f32 v91, v92, v93
	ds_write_b64 v219, v[90:91] offset:768
	v_cvt_pk_bf16_f32 v94, v94, v95
	v_cvt_pk_bf16_f32 v95, v96, v97
	ds_write_b64 v219, v[94:95] offset:896
	s_waitcnt vmcnt(32)
	v_cvt_pk_bf16_f32 v98, v98, v99
	v_cvt_pk_bf16_f32 v99, v100, v101
	ds_write_b64 v220, v[98:99]
	v_cvt_pk_bf16_f32 v102, v102, v103
	v_cvt_pk_bf16_f32 v103, v104, v105
	ds_write_b64 v220, v[102:103] offset:512
	v_cvt_pk_bf16_f32 v106, v106, v107
	v_cvt_pk_bf16_f32 v107, v108, v109
	ds_write_b64 v220, v[106:107] offset:1024
	v_cvt_pk_bf16_f32 v110, v110, v111
	v_cvt_pk_bf16_f32 v111, v112, v113
	ds_write_b64 v220, v[110:111] offset:1536
	v_cvt_pk_bf16_f32 v114, v114, v115
	v_cvt_pk_bf16_f32 v115, v116, v117
	ds_write_b64 v220, v[114:115] offset:2048
	v_cvt_pk_bf16_f32 v118, v118, v119
	v_cvt_pk_bf16_f32 v119, v120, v121
	ds_write_b64 v220, v[118:119] offset:2560
	v_cvt_pk_bf16_f32 v122, v122, v123
	v_cvt_pk_bf16_f32 v123, v124, v125
	ds_write_b64 v220, v[122:123] offset:3072
	v_cvt_pk_bf16_f32 v126, v126, v127
	v_cvt_pk_bf16_f32 v127, v128, v129
	ds_write_b64 v220, v[126:127] offset:3584
	global_load_dwordx4 v[66:69], v209, s[70:71] nt
	global_load_dwordx4 v[70:73], v210, s[70:71] nt
	global_load_dwordx4 v[74:77], v211, s[70:71] nt
	global_load_dwordx4 v[78:81], v212, s[70:71] nt
	global_load_dwordx4 v[82:85], v213, s[70:71] nt
	global_load_dwordx4 v[86:89], v214, s[70:71] nt
	global_load_dwordx4 v[90:93], v215, s[70:71] nt
	global_load_dwordx4 v[94:97], v218, s[70:71] nt
	global_load_dwordx4 v[98:101], v209, s[72:73] nt
	global_load_dwordx4 v[102:105], v210, s[72:73] nt
	global_load_dwordx4 v[106:109], v211, s[72:73] nt
	global_load_dwordx4 v[110:113], v212, s[72:73] nt
	global_load_dwordx4 v[114:117], v213, s[72:73] nt
	global_load_dwordx4 v[118:121], v214, s[72:73] nt
	global_load_dwordx4 v[122:125], v215, s[72:73] nt
	global_load_dwordx4 v[126:129], v218, s[72:73] nt
	s_add_u32 s70, s70, 0x20000
	s_addc_u32 s71, s71, 0
	s_add_u32 s72, s72, 0x20000
	s_addc_u32 s73, s73, 0
	s_waitcnt lgkmcnt(0)
	s_barrier
	s_mov_b32 s62, 19
